# RWKV scanner waves staggered per chunk (wave id x s_sleep 1) so their LDS operand read bursts do not collide
# speedup vs baseline: 1.0564x; 1.0212x over previous
.LBB0_388:
	s_or_b64 exec, exec, s[38:39]
	s_waitcnt vmcnt(0)
	v_lshlrev_b32_e32 v80, 16, v28
	v_and_b32_e32 v81, 0xffff0000, v28
	v_lshlrev_b32_e32 v82, 16, v29
	v_and_b32_e32 v83, 0xffff0000, v29
	v_lshlrev_b32_e32 v84, 16, v30
	v_and_b32_e32 v85, 0xffff0000, v30
	v_lshlrev_b32_e32 v86, 16, v31
	v_and_b32_e32 v87, 0xffff0000, v31
	v_lshlrev_b32_e32 v28, 16, v24
	v_and_b32_e32 v29, 0xffff0000, v24
	v_lshlrev_b32_e32 v30, 16, v25
	v_and_b32_e32 v31, 0xffff0000, v25
	v_lshlrev_b32_e32 v24, 3, v62
	v_and_b32_e32 v25, 0xff, v62
	v_lshlrev_b32_e32 v52, 16, v26
	v_and_b32_e32 v53, 0xffff0000, v26
	v_and_b32_e32 v24, 0xe00, v24
	v_mad_u32_u24 v26, v25, s33, 0
	s_add_i32 s50, s50, s42
	v_add_u32_e32 v124, 0, v24
	v_add_u32_e32 v125, 0xa800, v26
	v_add_u32_e32 v126, v111, v24
	v_mad_u32_u24 v127, v25, s33, v114
	v_add_u32_e32 v26, s50, v98
	v_lshlrev_b64 v[24:25], 1, v[66:67]
	v_mad_i64_i32 v[24:25], s[38:39], v26, s46, v[24:25]
	v_lshl_add_u64 v[60:61], s[28:29], 0, v[24:25]
	v_lshlrev_b64 v[24:25], 1, v[62:63]
	v_mad_i64_i32 v[24:25], s[38:39], v26, s45, v[24:25]
	v_readlane_b32 s38, v234, 9
	v_readlane_b32 s39, v234, 10
	v_lshlrev_b32_e32 v54, 16, v27
	v_and_b32_e32 v55, 0xffff0000, v27
	v_lshlrev_b32_e32 v56, 16, v32
	v_and_b32_e32 v57, 0xffff0000, v32
	v_lshlrev_b32_e32 v32, 16, v33
	v_and_b32_e32 v33, 0xffff0000, v33
	v_lshlrev_b32_e32 v58, 16, v34
	v_and_b32_e32 v59, 0xffff0000, v34
	v_lshlrev_b32_e32 v34, 16, v35
	v_and_b32_e32 v35, 0xffff0000, v35
	v_lshl_add_u64 v[62:63], s[38:39], 0, v[24:25]
	s_mov_b32 s54, 0
	global_load_dwordx4 v[236:239], v[62:63], off
	v_lshl_add_u64 v[252:253], v[62:63], 0, s[34:35]
	global_load_dwordx4 v[240:243], v[252:253], off
	v_lshl_add_u64 v[252:253], v[252:253], 0, s[34:35]
	global_load_dwordx4 v[240:243], v[252:253], off
	v_lshl_add_u64 v[252:253], v[252:253], 0, s[34:35]
	global_load_dwordx4 v[240:243], v[252:253], off
	v_lshl_add_u64 v[252:253], v[252:253], 0, s[34:35]
	global_load_dwordx4 v[240:243], v[252:253], off
	v_lshl_add_u64 v[252:253], v[252:253], 0, s[34:35]
	s_branch .LBB0_390

.LBB0_390:
	v_pk_fma_f32 v[78:79], v[38:39], v[80:81], v[36:37]
	v_pk_fma_f32 v[80:81], v[40:41], v[82:83], v[42:43]
	v_pk_fma_f32 v[82:83], v[44:45], v[84:85], v[46:47]
	v_pk_fma_f32 v[84:85], v[48:49], v[86:87], v[50:51]
	v_pk_fma_f32 v[78:79], v[0:1], v[28:29], v[78:79]
	v_pk_fma_f32 v[80:81], v[2:3], v[30:31], v[80:81]
	v_pk_fma_f32 v[82:83], v[8:9], v[52:53], v[82:83]
	v_pk_fma_f32 v[84:85], v[10:11], v[54:55], v[84:85]
	v_pk_fma_f32 v[86:87], v[4:5], v[56:57], v[78:79]
	v_pk_fma_f32 v[88:89], v[6:7], v[32:33], v[80:81]
	v_pk_fma_f32 v[90:91], v[12:13], v[58:59], v[82:83]
	v_pk_fma_f32 v[92:93], v[14:15], v[34:35], v[84:85]
	s_mov_b64 s[40:41], 0
	s_waitcnt vmcnt(2)
	v_lshlrev_b32_e32 v78, 16, v236
	v_and_b32_e32 v79, 0xffff0000, v236
	v_lshlrev_b32_e32 v80, 16, v237
	v_and_b32_e32 v81, 0xffff0000, v237
	v_lshlrev_b32_e32 v82, 16, v238
	v_and_b32_e32 v83, 0xffff0000, v238
	v_lshlrev_b32_e32 v84, 16, v239
	v_and_b32_e32 v85, 0xffff0000, v239
	v_lshl_add_u64 v[254:255], v[62:63], 0, s[34:35]
	global_load_dwordx4 v[236:239], v[254:255], off
	global_load_dwordx4 v[240:243], v[252:253], off
	v_lshl_add_u64 v[252:253], v[252:253], 0, s[34:35]
	v_pk_fma_f32 v[24:25], v[16:17], v[78:79], v[86:87]
	v_pk_fma_f32 v[26:27], v[18:19], v[80:81], v[88:89]
	v_pk_fma_f32 v[86:87], v[20:21], v[82:83], v[90:91]
	v_pk_fma_f32 v[128:129], v[22:23], v[84:85], v[92:93]
	v_mul_f32_e32 v66, 0xbfb8aa3b, v24
	v_mul_f32_e32 v88, 0xbfb8aa3b, v25
	v_mul_f32_e32 v89, 0xbfb8aa3b, v26
	v_mul_f32_e32 v90, 0xbfb8aa3b, v27
	v_mul_f32_e32 v91, 0xbfb8aa3b, v86
	v_mul_f32_e32 v92, 0xbfb8aa3b, v87
	v_mul_f32_e32 v93, 0xbfb8aa3b, v128
	v_mul_f32_e32 v130, 0xbfb8aa3b, v129
	v_exp_f32_e32 v66, v66
	v_exp_f32_e32 v88, v88
	v_exp_f32_e32 v89, v89
	v_exp_f32_e32 v90, v90
	v_exp_f32_e32 v91, v91
	v_exp_f32_e32 v92, v92
	v_exp_f32_e32 v93, v93
	v_exp_f32_e32 v130, v130
	v_add_f32_e32 v66, 1.0, v66
	v_add_f32_e32 v131, 1.0, v88
	v_add_f32_e32 v132, 1.0, v89
	v_add_f32_e32 v133, 1.0, v90
	v_add_f32_e32 v134, 1.0, v91
	v_add_f32_e32 v92, 1.0, v92
	v_add_f32_e32 v93, 1.0, v93
	v_add_f32_e32 v135, 1.0, v130
	v_rcp_f32_e32 v88, v66
	v_rcp_f32_e32 v89, v131
	v_rcp_f32_e32 v90, v132
	v_rcp_f32_e32 v91, v133
	v_rcp_f32_e32 v130, v134
	v_rcp_f32_e32 v131, v92
	v_rcp_f32_e32 v132, v93
	v_rcp_f32_e32 v133, v135
	v_pk_mul_f32 v[92:93], v[24:25], v[88:89]
	v_pk_mul_f32 v[90:91], v[26:27], v[90:91]
	v_pk_mul_f32 v[88:89], v[86:87], v[130:131]
	v_pk_mul_f32 v[86:87], v[128:129], v[132:133]
	v_cvt_pk_bf16_f32 v24, v92, v93
	v_cvt_pk_bf16_f32 v25, v90, v91
	v_cvt_pk_bf16_f32 v26, v88, v89
	v_cvt_pk_bf16_f32 v27, v86, v87
	global_store_dwordx4 v[60:61], v[24:27], off
	s_and_saveexec_b64 s[38:39], s[12:13]
	s_xor_b64 s[38:39], exec, s[38:39]
	s_cbranch_execnz .LBB0_393
	s_or_saveexec_b64 s[38:39], s[38:39]
	v_mov_b32_e32 v66, v125
	s_xor_b64 exec, exec, s[38:39]
	s_cbranch_execnz .LBB0_396

.LBB0_408:
	s_or_b64 exec, exec, s[36:37]
	v_lshlrev_b32_e32 v52, 9, v76
	s_waitcnt vmcnt(0)
	v_lshlrev_b32_e32 v54, 16, v40
	v_and_b32_e32 v55, 0xffff0000, v40
	v_lshlrev_b32_e32 v40, 3, v60
	v_add_lshl_u32 v53, v117, v52, 3
	v_or_b32_e32 v52, v119, v52
	v_and_b32_e32 v40, 0xe00, v40
	v_lshlrev_b32_e32 v66, 1, v52
	v_lshlrev_b32_e32 v78, 16, v46
	v_and_b32_e32 v79, 0xffff0000, v46
	v_lshlrev_b32_e32 v76, 16, v47
	v_and_b32_e32 v77, 0xffff0000, v47
	v_lshlrev_b32_e32 v46, 16, v42
	v_and_b32_e32 v47, 0xffff0000, v42
	v_add_u32_e32 v40, 0, v40
	v_add_u32_e32 v42, s50, v101
	v_lshlrev_b32_e32 v82, 16, v44
	v_and_b32_e32 v83, 0xffff0000, v44
	v_lshlrev_b32_e32 v80, 16, v45
	v_and_b32_e32 v81, 0xffff0000, v45
	v_lshlrev_b32_e32 v44, 16, v41
	v_and_b32_e32 v45, 0xffff0000, v41
	ds_read_b32 v93, v40 offset:4604
	v_mad_i64_i32 v[40:41], s[36:37], v42, s46, v[66:67]
	v_lshlrev_b32_e32 v62, 16, v48
	v_and_b32_e32 v63, 0xffff0000, v48
	v_lshlrev_b32_e32 v56, 16, v49
	v_and_b32_e32 v57, 0xffff0000, v49
	v_lshl_add_u64 v[48:49], s[28:29], 0, v[40:41]
	v_mad_i64_i32 v[40:41], s[36:37], v42, s45, 0
	v_readlane_b32 s36, v234, 9
	v_and_b32_e32 v53, 0xe00, v53
	v_lshl_or_b32 v40, v60, 1, v40
	v_readlane_b32 s37, v234, 10
	v_add_u32_e32 v92, v116, v53
	v_lshlrev_b32_e32 v52, 16, v43
	v_and_b32_e32 v53, 0xffff0000, v43
	v_lshlrev_b32_e32 v58, 16, v50
	v_and_b32_e32 v59, 0xffff0000, v50
	v_lshlrev_b32_e32 v50, 16, v51
	v_and_b32_e32 v51, 0xffff0000, v51
	v_lshl_add_u64 v[60:61], s[36:37], 0, v[40:41]
	s_mov_b32 s36, 0
	global_load_dwordx4 v[236:239], v[60:61], off
	v_lshl_add_u64 v[252:253], v[60:61], 0, s[34:35]
	global_load_dwordx4 v[240:243], v[252:253], off
	v_lshl_add_u64 v[252:253], v[252:253], 0, s[34:35]
	global_load_dwordx4 v[240:243], v[252:253], off
	v_lshl_add_u64 v[252:253], v[252:253], 0, s[34:35]
	global_load_dwordx4 v[240:243], v[252:253], off
	v_lshl_add_u64 v[252:253], v[252:253], 0, s[34:35]
	global_load_dwordx4 v[240:243], v[252:253], off
	v_lshl_add_u64 v[252:253], v[252:253], 0, s[34:35]
.LBB0_409:
	ds_read2st64_b32 v[126:127], v92 offset1:16
	v_pk_fma_f32 v[84:85], v[32:33], v[82:83], v[36:37]
	v_mov_b64_e32 v[82:83], v[54:55]
	v_pk_fma_f32 v[84:85], v[16:17], v[54:55], v[84:85]
	v_mov_b64_e32 v[54:55], v[62:63]
	v_pk_fma_f32 v[62:63], v[8:9], v[62:63], v[84:85]
	s_waitcnt lgkmcnt(0)
	v_sub_f32_e32 v84, v93, v127
	v_mul_f32_e32 v84, 0x3fb8aa3b, v84
	v_exp_f32_e32 v84, v84
	v_pk_fma_f32 v[86:87], v[34:35], v[80:81], v[38:39]
	v_pk_fma_f32 v[88:89], v[24:25], v[78:79], v[28:29]
	v_pk_fma_f32 v[124:125], v[26:27], v[76:77], v[30:31]
	v_pk_fma_f32 v[86:87], v[18:19], v[44:45], v[86:87]
	v_pk_fma_f32 v[88:89], v[0:1], v[46:47], v[88:89]
	v_pk_fma_f32 v[124:125], v[2:3], v[52:53], v[124:125]
	v_mov_b64_e32 v[76:77], v[52:53]
	v_mov_b64_e32 v[78:79], v[46:47]
	v_mov_b64_e32 v[80:81], v[44:45]
	v_mov_b64_e32 v[52:53], v[50:51]
	v_mov_b64_e32 v[46:47], v[58:59]
	v_mov_b64_e32 v[44:45], v[56:57]
	v_pk_fma_f32 v[56:57], v[10:11], v[56:57], v[86:87]
	v_pk_fma_f32 v[58:59], v[4:5], v[58:59], v[88:89]
	v_pk_fma_f32 v[50:51], v[6:7], v[50:51], v[124:125]
	v_mul_f32_e32 v123, v126, v84
	v_add_u32_e32 v66, s36, v118
	s_add_i32 s36, s36, 2
	v_add_u32_e32 v92, 4, v92
	v_lshl_add_u64 v[60:61], v[60:61], 0, s[34:35]
	s_cmp_lg_u32 s36, 16
	s_waitcnt vmcnt(2)
	v_lshlrev_b32_e32 v84, 16, v236
	v_and_b32_e32 v85, 0xffff0000, v236
	v_lshlrev_b32_e32 v40, 16, v237
	v_and_b32_e32 v41, 0xffff0000, v237
	v_lshlrev_b32_e32 v86, 16, v238
	v_and_b32_e32 v87, 0xffff0000, v238
	v_lshlrev_b32_e32 v42, 16, v239
	v_and_b32_e32 v43, 0xffff0000, v239
	global_load_dwordx4 v[236:239], v[60:61], off
	global_load_dwordx4 v[240:243], v[252:253], off
	v_lshl_add_u64 v[252:253], v[252:253], 0, s[34:35]
	v_pk_fma_f32 v[88:89], v[12:13], v[84:85], v[62:63]
	v_pk_fma_f32 v[124:125], v[14:15], v[40:41], v[56:57]
	v_pk_fma_f32 v[126:127], v[20:21], v[86:87], v[58:59]
	v_pk_fma_f32 v[128:129], v[22:23], v[42:43], v[50:51]
	v_mov_b64_e32 v[50:51], v[42:43]
	v_mov_b64_e32 v[58:59], v[86:87]
	v_mov_b64_e32 v[56:57], v[40:41]
	v_mov_b64_e32 v[62:63], v[84:85]
	v_mul_f32_e32 v40, 0xbfb8aa3b, v88
	v_mul_f32_e32 v41, 0xbfb8aa3b, v89
	v_mul_f32_e32 v42, 0xbfb8aa3b, v124
	v_mul_f32_e32 v43, 0xbfb8aa3b, v125
	v_mul_f32_e32 v84, 0xbfb8aa3b, v126
	v_mul_f32_e32 v85, 0xbfb8aa3b, v127
	v_mul_f32_e32 v86, 0xbfb8aa3b, v128
	v_mul_f32_e32 v87, 0xbfb8aa3b, v129
	v_exp_f32_e32 v40, v40
	v_exp_f32_e32 v41, v41
	v_exp_f32_e32 v42, v42
	v_exp_f32_e32 v43, v43
	v_exp_f32_e32 v84, v84
	v_exp_f32_e32 v85, v85
	v_exp_f32_e32 v86, v86
	v_exp_f32_e32 v87, v87
	v_add_f32_e32 v40, 1.0, v40
	v_add_f32_e32 v41, 1.0, v41
	v_add_f32_e32 v42, 1.0, v42
	v_add_f32_e32 v43, 1.0, v43
	v_add_f32_e32 v84, 1.0, v84
	v_add_f32_e32 v85, 1.0, v85
	v_add_f32_e32 v86, 1.0, v86
	v_add_f32_e32 v87, 1.0, v87
	v_rcp_f32_e32 v40, v40
	v_rcp_f32_e32 v41, v41
	v_rcp_f32_e32 v42, v42
	v_rcp_f32_e32 v43, v43
	v_rcp_f32_e32 v84, v84
	v_rcp_f32_e32 v85, v85
	v_rcp_f32_e32 v86, v86
	v_rcp_f32_e32 v87, v87
	v_pk_mul_f32 v[88:89], v[88:89], v[40:41]
	v_pk_mul_f32 v[124:125], v[124:125], v[42:43]
	v_pk_mul_f32 v[84:85], v[126:127], v[84:85]
	v_pk_mul_f32 v[86:87], v[128:129], v[86:87]
	v_cvt_pk_bf16_f32 v40, v88, v89
	v_cvt_pk_bf16_f32 v41, v124, v125
	v_cvt_pk_bf16_f32 v42, v84, v85
	v_cvt_pk_bf16_f32 v43, v86, v87
	v_mul_f32_e32 v88, v123, v88
	v_mul_f32_e32 v89, v123, v89
	v_mul_f32_e32 v124, v123, v124
	v_mul_f32_e32 v125, v123, v125
	v_mul_f32_e32 v84, v123, v84
	v_mul_f32_e32 v85, v123, v85
	v_mul_f32_e32 v86, v123, v86
	v_mul_f32_e32 v87, v123, v87
	global_store_dwordx4 v[48:49], v[40:43], off
	v_lshl_add_u64 v[48:49], v[48:49], 0, s[30:31]
	v_cvt_pk_bf16_f32 v84, v84, s0
	v_cvt_pk_bf16_f32 v40, v88, s0
	v_cvt_pk_bf16_f32 v41, v89, s0
	v_cvt_pk_bf16_f32 v42, v124, s0
	v_cvt_pk_bf16_f32 v43, v125, s0
	v_cvt_pk_bf16_f32 v85, v85, s0
	v_cvt_pk_bf16_f32 v86, v86, s0
	v_cvt_pk_bf16_f32 v87, v87, s0
	ds_write_b16 v66, v40
	ds_write_b16 v66, v41 offset:272
	ds_write_b16 v66, v42 offset:544
	ds_write_b16 v66, v43 offset:816
	ds_write_b16 v66, v84 offset:1088
	ds_write_b16 v66, v85 offset:1360
	ds_write_b16 v66, v86 offset:1632
	ds_write_b16 v66, v87 offset:1904
	s_cbranch_scc1 .LBB0_409
	s_waitcnt lgkmcnt(0)
	s_barrier
	ds_read_b128 v[0:3], v95 offset:8192
	ds_read_b128 v[4:7], v95 offset:8256
	ds_read_b128 v[8:11], v95 offset:12544
	ds_read_b128 v[12:15], v95 offset:12608
	ds_read_b128 v[16:19], v95 offset:16896
	ds_read_b128 v[20:23], v95 offset:16960
	ds_read_b128 v[24:27], v95 offset:21248
	ds_read_b128 v[28:31], v95 offset:21312
	ds_read_b128 v[32:35], v95 offset:8320
	ds_read_b128 v[36:39], v95 offset:8384
	ds_read_b128 v[40:43], v95 offset:12672
	ds_read_b128 v[44:47], v95 offset:12736
	ds_read_b128 v[48:51], v95 offset:17024
	ds_read_b128 v[52:55], v95 offset:17088
	ds_read_b128 v[56:59], v95 offset:21376
	ds_read_b128 v[60:63], v95 offset:21440
	v_add3_u32 v76, v120, v90, v91
	v_ashrrev_i32_e32 v77, 31, v76
	v_lshlrev_b64 v[76:77], 14, v[76:77]
	v_lshl_add_u64 v[76:77], v[74:75], 0, v[76:77]
	s_mov_b64 s[36:37], 0
	v_mov_b32_e32 v66, v115

.LBB0_724:
	s_and_b32 s16, s59, 3
	s_and_saveexec_b64 s[0:1], s[2:3]
	s_xor_b64 s[8:9], exec, s[0:1]
	s_cbranch_execz .LBB0_727
	v_mov_b32_e32 v2, 0
	v_lshl_add_u32 v0, s16, 6, v41
	s_mov_b32 s0, 0
	v_mov_b32_e32 v3, v2
	v_mov_b32_e32 v4, v2
	v_mov_b32_e32 v5, v2
	v_readfirstlane_b32 s98, v170
	s_nop 3
	s_lshr_b32 s98, s98, 6
	s_and_b32 s98, s98, 3
	s_barrier
.LBB0_726:
	s_mov_b32 s99, s98
.Lstag_loop:
	s_cmp_eq_u32 s99, 0
	s_cbranch_scc1 .Lstag_done
	s_sleep 1
	s_sub_u32 s99, s99, 1
	s_branch .Lstag_loop

.LBB0_730:
	s_or_b64 exec, exec, s[0:1]
	v_readlane_b32 s0, v234, 9
	v_readlane_b32 s1, v234, 10
	v_lshl_add_u64 v[6:7], s[34:35], 0, v[36:37]
	v_lshlrev_b64 v[2:3], 11, v[2:3]
	v_mov_b64_e32 v[8:9], s[0:1]
	v_mad_u64_u32 v[8:9], s[0:1], v6, s53, v[8:9]
	v_mad_i32_i24 v9, v7, s53, v9
	v_lshl_add_u64 v[8:9], v[8:9], 0, v[0:1]
	s_movk_i32 s0, 0x1000
	v_add_co_u32_e32 v60, vcc, s0, v8
	s_movk_i32 s0, 0x2000
	s_nop 0
	v_addc_co_u32_e32 v61, vcc, 0, v9, vcc
	v_add_co_u32_e32 v62, vcc, s0, v8
	s_movk_i32 s0, 0xf000
	s_nop 0
	v_addc_co_u32_e32 v63, vcc, 0, v9, vcc
	v_lshl_add_u64 v[4:5], s[10:11], 0, v[2:3]
	v_lshl_add_u64 v[2:3], s[12:13], 0, v[2:3]
	v_add_co_u32_e32 v64, vcc, s0, v8
	v_lshl_add_u64 v[4:5], v[4:5], 0, v[0:1]
	v_lshl_add_u64 v[2:3], v[2:3], 0, v[0:1]
	v_lshl_add_u64 v[58:59], v[8:9], 0, s[28:29]
	v_addc_co_u32_e32 v65, vcc, -1, v9, vcc
	global_load_dwordx2 v[86:87], v[60:61], off offset:1056
	global_load_dwordx2 v[88:89], v[62:63], off offset:1056
	global_load_dwordx2 v[98:99], v[64:65], off offset:-3040
	global_load_dwordx2 v[94:95], v[64:65], off offset:-992
	global_load_dwordx2 v[122:123], v[4:5], off
	global_load_dwordx2 v[120:121], v[2:3], off
	global_load_dwordx2 v[96:97], v[58:59], off offset:2048
	global_load_dwordx2 v[92:93], v[8:9], off offset:-3040
	v_lshlrev_b64 v[2:3], 11, v[6:7]
	v_lshl_add_u64 v[4:5], s[10:11], 0, v[2:3]
	v_lshl_add_u64 v[4:5], v[4:5], 0, v[0:1]
	v_lshl_add_u64 v[2:3], s[12:13], 0, v[2:3]
	v_lshl_add_u64 v[2:3], v[2:3], 0, v[0:1]
	global_load_dwordx2 v[90:91], v[4:5], off
	global_load_dwordx2 v[84:85], v[2:3], off
	s_lshr_b32 s0, s59, 2
	s_and_b32 s0, s0, 15
	s_lshl_b32 s40, s0, 2
	s_cmp_eq_u32 s59, s71
	v_lshlrev_b32_e32 v0, 1, v43
	s_cselect_b64 s[36:37], -1, 0
	s_cmp_eq_u32 s16, 0
	v_lshl_or_b32 v2, s0, 7, v0
	s_cselect_b64 s[38:39], -1, 0
	s_lshl_b32 s0, s60, 1
	s_add_u32 s0, s14, s0
	s_addc_u32 s1, s15, 0
	s_lshl_b32 s61, s16, 4
	s_lshl_b32 s16, s16, 5
	s_add_u32 s0, s0, s16
	s_addc_u32 s1, s1, 0
	v_lshlrev_b32_e32 v58, 1, v46
	v_mov_b32_e32 v59, v1
	v_lshl_add_u64 v[72:73], s[0:1], 0, v[58:59]
	s_lshl_b64 s[0:1], s[8:9], 18
	s_or_b32 s0, s0, s40
	v_lshl_add_u64 v[78:79], s[0:1], 0, v[50:51]
	s_lshl_b64 s[0:1], s[8:9], 23
	v_mov_b32_e32 v3, v1
	v_lshl_add_u64 v[4:5], v[52:53], 0, s[0:1]
	v_lshl_add_u64 v[80:81], v[4:5], 0, v[2:3]
	v_mad_i64_i32 v[4:5], s[0:1], s8, v152, v[54:55]
	v_lshl_add_u64 v[82:83], v[4:5], 0, v[2:3]
	v_mov_b32_e32 v2, v1
	v_mov_b32_e32 v4, v1
	v_mov_b32_e32 v5, v1
	v_mov_b32_e32 v6, v1
	v_mov_b32_e32 v7, v1
	v_mov_b32_e32 v0, v1
	v_mov_b64_e32 v[8:9], v[6:7]
	s_mov_b32 s62, 0
	v_lshl_add_u64 v[70:71], s[34:35], 0, v[44:45]
	s_waitcnt vmcnt(17)
	v_mov_b32_e32 v74, v16
	s_waitcnt vmcnt(13)
	v_mov_b32_e32 v75, v33
	v_mov_b32_e32 v76, v29
	v_mov_b32_e32 v77, v57
	v_mov_b64_e32 v[62:63], 0
	s_movk_i32 s16, 0xffc0
	v_mov_b32_e32 v67, 0
	v_mov_b32_e32 v33, 0
	v_mov_b32_e32 v68, 0
	v_mov_b32_e32 v66, 0
	v_mov_b32_e32 v59, 0
	v_mov_b32_e32 v29, v47
	s_mov_b32 s63, 0
	v_mov_b64_e32 v[6:7], v[4:5]
	v_mov_b64_e32 v[4:5], v[2:3]
	v_mov_b64_e32 v[2:3], v[0:1]
	v_mov_b64_e32 v[64:65], 0
	v_mov_b64_e32 v[60:61], 0
	s_waitcnt vmcnt(0)

.LBB0_748:
	s_or_b64 exec, exec, s[44:45]
	v_lshl_or_b32 v0, v67, 4, v137
	v_add_u32_e32 v4, v0, v66
	v_ashrrev_i32_e32 v69, 31, v68
	v_lshl_add_u64 v[2:3], v[68:69], 2, v[62:63]
	v_lshlrev_b32_e32 v0, 2, v38
	v_mad_u64_u32 v[6:7], s[0:1], v4, v59, 0
	v_lshl_add_u64 v[2:3], v[2:3], 0, v[0:1]
	v_ashrrev_i32_e32 v5, 31, v4
	v_mov_b32_e32 v0, v7
	v_mad_u64_u32 v[8:9], s[0:1], v5, v59, v[0:1]
	v_mov_b32_e32 v7, v8
	v_lshl_add_u64 v[6:7], v[6:7], 2, v[2:3]
	global_load_dword v236, v[6:7], off nt
	v_cmp_ne_u64_e32 vcc, 0, v[60:61]
	v_mov_b32_e32 v245, 1.0
	v_lshl_add_u64 v[6:7], v[4:5], 2, v[60:61]
	v_mov_b32_e32 v244, 1.0
	s_and_saveexec_b64 s[0:1], vcc
	s_cbranch_execz .LBB0_750
	global_load_dword v244, v[6:7], off
.LBB0_750:
	s_or_b64 exec, exec, s[0:1]
	v_add_u32_e32 v9, 2, v4
	v_mad_u64_u32 v[112:113], s[0:1], v9, v59, 0
	v_ashrrev_i32_e32 v56, 31, v9
	v_mov_b32_e32 v16, v113
	v_mad_u64_u32 v[114:115], s[0:1], v56, v59, v[16:17]
	v_mov_b32_e32 v113, v114
	v_lshl_add_u64 v[112:113], v[112:113], 2, v[2:3]
	global_load_dword v237, v[112:113], off nt
	s_and_saveexec_b64 s[0:1], vcc
	s_cbranch_execz .LBB0_752
	global_load_dword v245, v[6:7], off offset:8
.LBB0_752:
	s_or_b64 exec, exec, s[0:1]
	v_add_u32_e32 v16, 4, v4
	v_mad_u64_u32 v[112:113], s[0:1], v16, v59, 0
	v_ashrrev_i32_e32 v56, 31, v16
	v_mov_b32_e32 v16, v113
	v_mad_u64_u32 v[114:115], s[0:1], v56, v59, v[16:17]
	v_mov_b32_e32 v113, v114
	v_lshl_add_u64 v[112:113], v[112:113], 2, v[2:3]
	global_load_dword v238, v[112:113], off nt
	v_mov_b32_e32 v247, 1.0
	v_mov_b32_e32 v246, 1.0
	s_and_saveexec_b64 s[0:1], vcc
	s_cbranch_execz .LBB0_754
	global_load_dword v246, v[6:7], off offset:16
.LBB0_754:
	s_or_b64 exec, exec, s[0:1]
	v_add_u32_e32 v112, 6, v4
	v_ashrrev_i32_e32 v115, 31, v112
	v_mad_u64_u32 v[112:113], s[0:1], v112, v59, 0
	v_mov_b32_e32 v114, v113
	v_mad_u64_u32 v[114:115], s[0:1], v115, v59, v[114:115]
	v_mov_b32_e32 v113, v114
	v_lshl_add_u64 v[112:113], v[112:113], 2, v[2:3]
	global_load_dword v239, v[112:113], off nt
	s_and_saveexec_b64 s[0:1], vcc
	s_cbranch_execz .LBB0_756
	global_load_dword v247, v[6:7], off offset:24
.LBB0_756:
	s_or_b64 exec, exec, s[0:1]
	v_add_u32_e32 v113, 8, v4
	v_mad_u64_u32 v[114:115], s[0:1], v113, v59, 0
	v_ashrrev_i32_e32 v117, 31, v113
	v_mov_b32_e32 v116, v115
	v_mad_u64_u32 v[116:117], s[0:1], v117, v59, v[116:117]
	v_mov_b32_e32 v115, v116
	v_lshl_add_u64 v[114:115], v[114:115], 2, v[2:3]
	global_load_dword v240, v[114:115], off nt
	v_mov_b32_e32 v249, 1.0
	v_mov_b32_e32 v248, 1.0
	s_and_saveexec_b64 s[0:1], vcc
	s_cbranch_execz .LBB0_758
	global_load_dword v248, v[6:7], off offset:32
.LBB0_758:
	s_or_b64 exec, exec, s[0:1]
	v_add_u32_e32 v116, 10, v4
	v_ashrrev_i32_e32 v119, 31, v116
	v_mad_u64_u32 v[116:117], s[0:1], v116, v59, 0
	v_mov_b32_e32 v118, v117
	v_mad_u64_u32 v[118:119], s[0:1], v119, v59, v[118:119]
	v_mov_b32_e32 v117, v118
	v_lshl_add_u64 v[116:117], v[116:117], 2, v[2:3]
	global_load_dword v241, v[116:117], off nt
	s_and_saveexec_b64 s[0:1], vcc
	s_cbranch_execz .LBB0_760
	global_load_dword v249, v[6:7], off offset:40
.LBB0_760:
	s_or_b64 exec, exec, s[0:1]
	v_add_u32_e32 v117, 12, v4
	v_mad_u64_u32 v[118:119], s[0:1], v117, v59, 0
	v_ashrrev_i32_e32 v125, 31, v117
	v_mov_b32_e32 v124, v119
	v_mad_u64_u32 v[124:125], s[0:1], v125, v59, v[124:125]
	v_mov_b32_e32 v119, v124
	v_lshl_add_u64 v[118:119], v[118:119], 2, v[2:3]
	global_load_dword v242, v[118:119], off nt
	v_mov_b32_e32 v251, 1.0
	v_mov_b32_e32 v250, 1.0
	s_and_saveexec_b64 s[0:1], vcc
	s_cbranch_execz .LBB0_762
	global_load_dword v250, v[6:7], off offset:48
.LBB0_762:
	s_or_b64 exec, exec, s[0:1]
	v_add_u32_e32 v4, 14, v4
	v_mad_u64_u32 v[124:125], s[0:1], v4, v59, 0
	v_ashrrev_i32_e32 v126, 31, v4
	v_mov_b32_e32 v4, v125
	v_mad_u64_u32 v[126:127], s[0:1], v126, v59, v[4:5]
	v_mov_b32_e32 v125, v126
	v_lshl_add_u64 v[2:3], v[124:125], 2, v[2:3]
	global_load_dword v243, v[2:3], off nt
	s_and_saveexec_b64 s[0:1], vcc
	s_cbranch_execz .LBB0_764
	global_load_dword v251, v[6:7], off offset:56

.LBB0_765:
	s_or_b64 exec, exec, s[8:9]
	s_cmp_eq_u32 s62, 0x10000
	s_cbranch_scc1 .LBB0_777
	s_cmpk_lt_u32 s63, 0x7f
	s_cselect_b64 s[44:45], -1, 0
	s_cmpk_gt_u32 s63, 0x7e
	v_lshl_add_u64 v[134:135], s[66:67], 0, v[82:83]
	v_lshl_add_u64 v[132:133], s[66:67], 0, v[80:81]
	v_mov_b64_e32 v[130:131], v[120:121]
	v_mov_b64_e32 v[128:129], v[122:123]
	v_mov_b64_e32 v[126:127], v[106:107]
	v_mov_b64_e32 v[118:119], v[102:103]
	v_mov_b64_e32 v[124:125], v[108:109]
	v_mov_b64_e32 v[114:115], v[104:105]
	v_mov_b64_e32 v[116:117], v[110:111]
	v_mov_b64_e32 v[112:113], v[100:101]
	s_cbranch_scc1 .LBB0_768
	v_add_co_u32_e32 v114, vcc, 0xd061000, v134
	s_nop 1
	v_addc_co_u32_e32 v115, vcc, 0, v135, vcc
	v_add_co_u32_e32 v116, vcc, 0xd062000, v134
	s_nop 1
	v_addc_co_u32_e32 v117, vcc, 0, v135, vcc
	v_add_co_u32_e32 v124, vcc, 0xd05e000, v134
	s_nop 1
	v_addc_co_u32_e32 v125, vcc, 0, v135, vcc
	v_add_co_u32_e32 v126, vcc, 0xd05f000, v134
	global_load_dwordx2 v[112:113], v[114:115], off offset:1056
	s_nop 0
	global_load_dwordx2 v[114:115], v[114:115], off offset:3104
	s_nop 0
	global_load_dwordx2 v[118:119], v[116:117], off offset:1056
	s_nop 0
	global_load_dwordx2 v[116:117], v[124:125], off offset:1056
	v_addc_co_u32_e32 v127, vcc, 0, v135, vcc
	v_add_co_u32_e32 v128, vcc, 0x19010000, v132
	s_nop 1
	v_addc_co_u32_e32 v129, vcc, 0, v133, vcc
	v_add_co_u32_e32 v130, vcc, 0x1b010000, v132
	s_nop 1
	v_addc_co_u32_e32 v131, vcc, 0, v133, vcc
	global_load_dwordx2 v[124:125], v[124:125], off offset:3104
	s_nop 0
	global_load_dwordx2 v[126:127], v[126:127], off offset:1056
	s_nop 0
	global_load_dwordx2 v[128:129], v[128:129], off
	s_nop 0
	global_load_dwordx2 v[130:131], v[130:131], off

.LBB0_771:
	s_or_b64 exec, exec, s[0:1]
	s_andn2_b64 vcc, exec, s[44:45]
	v_mov_b64_e32 v[122:123], v[84:85]
	v_mov_b64_e32 v[120:121], v[90:91]
	v_mov_b64_e32 v[110:111], v[92:93]
	v_mov_b64_e32 v[106:107], v[88:89]
	v_mov_b64_e32 v[108:109], v[94:95]
	v_mov_b64_e32 v[102:103], v[96:97]
	v_mov_b64_e32 v[104:105], v[98:99]
	v_mov_b64_e32 v[100:101], v[86:87]
	s_cbranch_vccnz .LBB0_773
	v_add_co_u32_e32 v102, vcc, 0xd091000, v134
	s_nop 1
	v_addc_co_u32_e32 v103, vcc, 0, v135, vcc
	v_add_co_u32_e32 v104, vcc, 0xd092000, v134
	s_nop 1
	v_addc_co_u32_e32 v105, vcc, 0, v135, vcc
	v_add_co_u32_e32 v108, vcc, 0xd08e000, v134
	s_nop 1
	v_addc_co_u32_e32 v109, vcc, 0, v135, vcc
	v_add_co_u32_e32 v110, vcc, 0xd08f000, v134
	global_load_dwordx2 v[100:101], v[102:103], off offset:1056
	s_nop 0
	global_load_dwordx2 v[102:103], v[102:103], off offset:3104
	s_nop 0
	global_load_dwordx2 v[106:107], v[104:105], off offset:1056
	s_nop 0
	global_load_dwordx2 v[104:105], v[108:109], off offset:1056
	v_addc_co_u32_e32 v111, vcc, 0, v135, vcc
	v_add_co_u32_e32 v120, vcc, 0x19018000, v132
	s_nop 1
	v_addc_co_u32_e32 v121, vcc, 0, v133, vcc
	v_add_co_u32_e32 v122, vcc, 0x1b018000, v132
	s_nop 1
	v_addc_co_u32_e32 v123, vcc, 0, v133, vcc
	global_load_dwordx2 v[108:109], v[108:109], off offset:3104
	s_nop 0
	global_load_dwordx2 v[110:111], v[110:111], off offset:1056
	s_nop 0
	global_load_dwordx2 v[120:121], v[120:121], off
	s_nop 0
	global_load_dwordx2 v[122:123], v[122:123], off

.LBB0_778:
	s_cmp_lg_u64 s[44:45], 0
	s_cbranch_scc0 .Lprod_late_w0
	s_waitcnt vmcnt(16)
	s_branch .Lprod_late_go

.Lprod_late_go:
	v_mul_f32_e32 v2, v236, v244
	v_mul_f32_e32 v3, v237, v245
	v_mul_f32_e32 v4, v238, v246
	v_mul_f32_e32 v5, v239, v247
	v_mul_f32_e32 v6, v240, v248
	v_mul_f32_e32 v7, v241, v249
	v_mul_f32_e32 v8, v242, v250
	v_mul_f32_e32 v9, v243, v251
	v_lshl_or_b32 v0, v67, 4, v137
	v_mad_u64_u32 v[84:85], s[0:1], v0, s52, v[40:41]
	v_add_u32_e32 v67, 1, v67
	v_add_u32_e32 v0, 0x400, v84
	v_cmp_eq_u32_e32 vcc, 4, v67
	ds_write2_b32 v84, v2, v3 offset1:66
	ds_write2_b32 v84, v4, v5 offset0:132 offset1:198
	ds_write2_b32 v0, v6, v7 offset0:8 offset1:74
	ds_write2_b32 v0, v8, v9 offset0:140 offset1:206
	s_and_saveexec_b64 s[42:43], vcc
	s_cbranch_execz .LBB0_780
	v_add_u32_e32 v0, v68, v139
	v_mad_u64_u32 v[154:155], s[0:1], v0, v33, 0
	ds_read2_b32 v[88:89], v140 offset0:33 offset1:41
	ds_read2_b32 v[90:91], v140 offset1:8
	ds_read2_b32 v[92:93], v140 offset0:66 offset1:74
	ds_read2_b32 v[94:95], v140 offset0:99 offset1:107
	ds_read2_b32 v[96:97], v140 offset0:132 offset1:140
	ds_read2_b32 v[98:99], v140 offset0:165 offset1:173
	ds_read2_b32 v[132:133], v140 offset0:198 offset1:206
	ds_read2_b32 v[134:135], v140 offset0:231 offset1:239
	v_ashrrev_i32_e32 v16, 31, v0
	v_mov_b32_e32 v0, v155
	v_mad_u64_u32 v[156:157], s[0:1], v16, v33, v[0:1]
	v_mov_b32_e32 v155, v156
	v_ashrrev_i32_e32 v67, 31, v66
	v_lshl_add_u64 v[154:155], v[154:155], 1, v[64:65]
	v_lshlrev_b64 v[156:157], 1, v[66:67]
	v_lshl_add_u64 v[154:155], v[154:155], 0, v[156:157]
	v_lshlrev_b32_e32 v0, 1, v42
	s_waitcnt lgkmcnt(6)
	v_cvt_pk_bf16_f32 v84, v90, v88
	s_waitcnt lgkmcnt(4)
	v_cvt_pk_bf16_f32 v85, v92, v94
	s_waitcnt lgkmcnt(2)
	v_cvt_pk_bf16_f32 v86, v96, v98
	s_waitcnt lgkmcnt(0)
	v_cvt_pk_bf16_f32 v87, v132, v134
	v_lshl_add_u64 v[154:155], v[154:155], 0, v[0:1]
	v_add_u32_e32 v16, v68, v141
	global_store_dwordx4 v[154:155], v[84:87], off nt
	v_ashrrev_i32_e32 v56, 31, v16
	v_add_u32_e32 v29, s33, v29
	v_cvt_pk_bf16_f32 v84, v91, v89
	v_mad_u64_u32 v[88:89], s[0:1], v16, v33, 0
	v_mov_b32_e32 v16, v89
	v_mad_u64_u32 v[90:91], s[0:1], v56, v33, v[16:17]
	v_mov_b32_e32 v89, v90
	v_lshl_add_u64 v[88:89], v[88:89], 1, v[64:65]
	v_lshl_add_u64 v[88:89], v[88:89], 0, v[156:157]
	v_cvt_pk_bf16_f32 v85, v93, v95
	v_cvt_pk_bf16_f32 v86, v97, v99
	v_cvt_pk_bf16_f32 v87, v133, v135
	v_lshl_add_u64 v[88:89], v[88:89], 0, v[0:1]
	v_add_u32_e32 v16, v68, v142
	global_store_dwordx4 v[88:89], v[84:87], off nt
	v_mad_u64_u32 v[154:155], s[0:1], v16, v33, 0
	ds_read2_b32 v[88:89], v140 offset0:16 offset1:24
	ds_read2_b32 v[90:91], v140 offset0:49 offset1:57
	ds_read2_b32 v[92:93], v140 offset0:82 offset1:90
	ds_read2_b32 v[94:95], v140 offset0:115 offset1:123
	ds_read2_b32 v[96:97], v140 offset0:148 offset1:156
	ds_read2_b32 v[98:99], v140 offset0:181 offset1:189
	ds_read2_b32 v[132:133], v140 offset0:214 offset1:222
	ds_read2_b32 v[134:135], v140 offset0:247 offset1:255
	v_ashrrev_i32_e32 v56, 31, v16
	v_mov_b32_e32 v16, v155
	v_mad_u64_u32 v[158:159], s[0:1], v56, v33, v[16:17]
	v_mov_b32_e32 v155, v158
	v_lshl_add_u64 v[154:155], v[154:155], 1, v[64:65]
	v_lshl_add_u64 v[154:155], v[154:155], 0, v[156:157]
	s_waitcnt lgkmcnt(6)
	v_cvt_pk_bf16_f32 v84, v88, v90
	s_waitcnt lgkmcnt(4)
	v_cvt_pk_bf16_f32 v85, v92, v94
	s_waitcnt lgkmcnt(2)
	v_cvt_pk_bf16_f32 v86, v96, v98
	s_waitcnt lgkmcnt(0)
	v_cvt_pk_bf16_f32 v87, v132, v134
	v_lshl_add_u64 v[154:155], v[154:155], 0, v[0:1]
	v_add_u32_e32 v16, v68, v143
	global_store_dwordx4 v[154:155], v[84:87], off nt
	v_ashrrev_i32_e32 v56, 31, v16
	v_mov_b32_e32 v67, 0
	v_cvt_pk_bf16_f32 v84, v89, v91
	v_mad_u64_u32 v[88:89], s[0:1], v16, v33, 0
	v_mov_b32_e32 v16, v89
	v_mad_u64_u32 v[90:91], s[0:1], v56, v33, v[16:17]
	v_mov_b32_e32 v89, v90
	v_lshl_add_u64 v[88:89], v[88:89], 1, v[64:65]
	v_lshl_add_u64 v[88:89], v[88:89], 0, v[156:157]
	v_cvt_pk_bf16_f32 v85, v93, v95
	v_cvt_pk_bf16_f32 v86, v97, v99
	v_cvt_pk_bf16_f32 v87, v133, v135
	v_lshl_add_u64 v[88:89], v[88:89], 0, v[0:1]
	global_store_dwordx4 v[88:89], v[84:87], off nt
